# regenerated MLA loop body with the QK MFMAs issued k-slice-major (four independent accumulator chains instead of back-to-back dependent triples)
# speedup vs baseline: 1.0026x; 1.0026x over previous
.LBB0_559:
	s_and_b32 s5, s4, 0x80
	v_or_b32_e32 v201, s5, v125
	v_mad_u32_u24 v201, v201, s12, v0
	v_or_b32_e32 v200, s5, v132
	v_mul_u32_u24_e32 v200, 0x48, v200
	v_lshl_add_u32 v200, v200, 1, v130
	ds_read_b128 v[164:167], v201 offset:0
	ds_read_b128 v[176:179], v201 offset:3328
	ds_read_b128 v[232:235], v201 offset:6656
	ds_read_b128 v[244:247], v201 offset:9984
	ds_read_b128 v[168:171], v201 offset:64
	ds_read_b128 v[180:183], v201 offset:3392
	ds_read_b128 v[236:239], v201 offset:6720
	ds_read_b128 v[142:145], v201 offset:10048
	ds_read_b128 v[172:175], v201 offset:128
	ds_read_b128 v[184:187], v201 offset:3456
	ds_read_b128 v[240:243], v201 offset:6784
	ds_read_b128 v[146:149], v201 offset:10112
	s_waitcnt lgkmcnt(11)
	v_mfma_f32_16x16x32_bf16 v[78:81], v[164:167], v[2:5], 0
	s_waitcnt lgkmcnt(10)
	v_mfma_f32_16x16x32_bf16 v[82:85], v[176:179], v[2:5], 0
	s_waitcnt lgkmcnt(9)
	v_mfma_f32_16x16x32_bf16 v[86:89], v[232:235], v[2:5], 0
	s_waitcnt lgkmcnt(8)
	v_mfma_f32_16x16x32_bf16 v[90:93], v[244:247], v[2:5], 0
	s_waitcnt lgkmcnt(7)
	v_mfma_f32_16x16x32_bf16 v[78:81], v[168:171], v[6:9], v[78:81]
	s_waitcnt lgkmcnt(6)
	v_mfma_f32_16x16x32_bf16 v[82:85], v[180:183], v[6:9], v[82:85]
	s_waitcnt lgkmcnt(5)
	v_mfma_f32_16x16x32_bf16 v[86:89], v[236:239], v[6:9], v[86:89]
	s_waitcnt lgkmcnt(4)
	v_mfma_f32_16x16x32_bf16 v[90:93], v[142:145], v[6:9], v[90:93]
	s_waitcnt lgkmcnt(3)
	v_mfma_f32_16x16x32_bf16 v[78:81], v[172:175], v[38:41], v[78:81]
	s_waitcnt lgkmcnt(2)
	v_mfma_f32_16x16x32_bf16 v[82:85], v[184:187], v[38:41], v[82:85]
	s_waitcnt lgkmcnt(1)
	v_mfma_f32_16x16x32_bf16 v[86:89], v[240:243], v[38:41], v[86:89]
	s_waitcnt lgkmcnt(0)
	v_mfma_f32_16x16x32_bf16 v[90:93], v[146:149], v[38:41], v[90:93]
	v_mfma_f32_16x16x32_bf16 v[94:97], v[164:167], v[26:29], 0
	s_nop 0
	v_max3_f32 v150, v78, s18, v79
	v_max3_f32 v150, v150, v80, v81
	v_max3_f32 v150, v150, v82, v83
	v_max3_f32 v150, v150, v84, v85
	v_max3_f32 v150, v150, v86, v87
	v_max3_f32 v150, v150, v88, v89
	v_max3_f32 v150, v150, v90, v91
	v_mfma_f32_16x16x32_bf16 v[98:101], v[176:179], v[26:29], 0
	v_max3_f32 v150, v150, v92, v93
	v_mul_f32_e32 v150, 0x3e16c740, v150
	v_mov_b32_e32 v152, v150
	s_nop 1
	v_permlane16_swap_b32_e32 v152, v150
	v_max_f32_e32 v150, v150, v152
	v_mov_b32_e32 v152, v150
	s_nop 1
	v_permlane32_swap_b32_e32 v152, v150
	v_mfma_f32_16x16x32_bf16 v[102:105], v[232:235], v[26:29], 0
	v_max_f32_e32 v150, v150, v152
	v_add_f32_e32 v154, 0x41000000, v139
	v_cmp_gt_f32_e32 vcc, v150, v154
	s_cbranch_vccz .Lmla_s0_keep0
	v_max_f32_e32 v158, v139, v150
	v_sub_f32_e32 v154, v139, v158
	v_exp_f32_e32 v154, v154
	v_mov_b32_e32 v139, v158
	v_mul_f32_e32 v141, v141, v154
	v_pk_mul_f32 v[74:75], v[74:75], v[154:155] op_sel_hi:[1,0]
	v_pk_mul_f32 v[76:77], v[76:77], v[154:155] op_sel_hi:[1,0]
	v_pk_mul_f32 v[70:71], v[70:71], v[154:155] op_sel_hi:[1,0]
	v_pk_mul_f32 v[72:73], v[72:73], v[154:155] op_sel_hi:[1,0]
	v_pk_mul_f32 v[66:67], v[66:67], v[154:155] op_sel_hi:[1,0]
	v_pk_mul_f32 v[68:69], v[68:69], v[154:155] op_sel_hi:[1,0]
	v_pk_mul_f32 v[62:63], v[62:63], v[154:155] op_sel_hi:[1,0]
	v_pk_mul_f32 v[64:65], v[64:65], v[154:155] op_sel_hi:[1,0]
.Lmla_s0_keep0:
	v_fma_f32 v78, v78, s21, -v139
	v_fma_f32 v79, v79, s21, -v139
	v_exp_f32_e32 v78, v78
	v_fma_f32 v80, v80, s21, -v139
	v_exp_f32_e32 v79, v79
	v_mfma_f32_16x16x32_bf16 v[106:109], v[244:247], v[26:29], 0
	v_fma_f32 v81, v81, s21, -v139
	v_exp_f32_e32 v80, v80
	v_exp_f32_e32 v81, v81
	v_fma_f32 v82, v82, s21, -v139
	v_fma_f32 v83, v83, s21, -v139
	v_exp_f32_e32 v82, v82
	v_fma_f32 v84, v84, s21, -v139
	v_mfma_f32_16x16x32_bf16 v[94:97], v[168:171], v[30:33], v[94:97]
	v_exp_f32_e32 v83, v83
	v_fma_f32 v85, v85, s21, -v139
	v_exp_f32_e32 v84, v84
	v_exp_f32_e32 v85, v85
	v_add_f32_e32 v160, 0, v78
	v_add_f32_e32 v160, v79, v160
	v_add_f32_e32 v160, v80, v160
	v_mfma_f32_16x16x32_bf16 v[98:101], v[180:183], v[30:33], v[98:101]
	v_add_f32_e32 v160, v81, v160
	v_cvt_pk_bf16_f32 v78, v78, v79
	v_cvt_pk_bf16_f32 v79, v80, v81
	v_fma_f32 v86, v86, s21, -v139
	v_fma_f32 v87, v87, s21, -v139
	v_exp_f32_e32 v86, v86
	v_fma_f32 v88, v88, s21, -v139
	v_mfma_f32_16x16x32_bf16 v[102:105], v[236:239], v[30:33], v[102:105]
	v_exp_f32_e32 v87, v87
	v_fma_f32 v89, v89, s21, -v139
	v_exp_f32_e32 v88, v88
	v_exp_f32_e32 v89, v89
	v_add_f32_e32 v160, v82, v160
	v_add_f32_e32 v160, v83, v160
	v_add_f32_e32 v160, v84, v160
	v_mfma_f32_16x16x32_bf16 v[106:109], v[142:145], v[30:33], v[106:109]
	v_add_f32_e32 v160, v85, v160
	v_cvt_pk_bf16_f32 v80, v82, v83
	v_cvt_pk_bf16_f32 v81, v84, v85
	v_fma_f32 v90, v90, s21, -v139
	v_fma_f32 v91, v91, s21, -v139
	v_exp_f32_e32 v90, v90
	v_fma_f32 v92, v92, s21, -v139
	v_mfma_f32_16x16x32_bf16 v[94:97], v[172:175], v[42:45], v[94:97]
	v_exp_f32_e32 v91, v91
	v_fma_f32 v93, v93, s21, -v139
	v_exp_f32_e32 v92, v92
	v_exp_f32_e32 v93, v93
	v_add_f32_e32 v160, v86, v160
	v_add_f32_e32 v160, v87, v160
	v_add_f32_e32 v160, v88, v160
	v_mfma_f32_16x16x32_bf16 v[98:101], v[184:187], v[42:45], v[98:101]
	v_add_f32_e32 v160, v89, v160
	v_cvt_pk_bf16_f32 v82, v86, v87
	v_cvt_pk_bf16_f32 v83, v88, v89
	v_add_f32_e32 v160, v90, v160
	v_add_f32_e32 v160, v91, v160
	v_add_f32_e32 v160, v92, v160
	v_add_f32_e32 v160, v93, v160
	v_mfma_f32_16x16x32_bf16 v[102:105], v[240:243], v[42:45], v[102:105]
	v_cvt_pk_bf16_f32 v84, v90, v91
	v_cvt_pk_bf16_f32 v85, v92, v93
	v_add_f32_e32 v141, v141, v160
	v_mfma_f32_16x16x32_bf16 v[106:109], v[146:149], v[42:45], v[106:109]
	s_waitcnt lgkmcnt(0)
	ds_read_b64_tr_b16 v[164:165], v200 offset:53248
	ds_read_b64_tr_b16 v[166:167], v200 offset:55552
	ds_read_b64_tr_b16 v[168:169], v200 offset:53280
	ds_read_b64_tr_b16 v[170:171], v200 offset:55584
	ds_read_b64_tr_b16 v[172:173], v200 offset:57856
	ds_read_b64_tr_b16 v[174:175], v200 offset:60160
	ds_read_b64_tr_b16 v[176:177], v200 offset:57888
	ds_read_b64_tr_b16 v[178:179], v200 offset:60192
	v_max3_f32 v151, v94, s18, v95
	v_max3_f32 v151, v151, v96, v97
	v_max3_f32 v151, v151, v98, v99
	v_max3_f32 v151, v151, v100, v101
	v_max3_f32 v151, v151, v102, v103
	v_max3_f32 v151, v151, v104, v105
	v_max3_f32 v151, v151, v106, v107
	v_max3_f32 v151, v151, v108, v109
	v_mul_f32_e32 v151, 0x3e16c740, v151
	v_mov_b32_e32 v153, v151
	s_nop 1
	v_permlane16_swap_b32_e32 v153, v151
	v_max_f32_e32 v151, v151, v153
	v_mov_b32_e32 v153, v151
	s_nop 1
	v_permlane32_swap_b32_e32 v153, v151
	v_max_f32_e32 v151, v151, v153
	s_waitcnt lgkmcnt(6)
	ds_read_b64_tr_b16 v[232:233], v200 offset:53312
	ds_read_b64_tr_b16 v[234:235], v200 offset:55616
	ds_read_b64_tr_b16 v[236:237], v200 offset:53344
	ds_read_b64_tr_b16 v[238:239], v200 offset:55648
	ds_read_b64_tr_b16 v[240:241], v200 offset:57920
	ds_read_b64_tr_b16 v[242:243], v200 offset:60224
	ds_read_b64_tr_b16 v[244:245], v200 offset:57952
	ds_read_b64_tr_b16 v[246:247], v200 offset:60256
	v_mfma_f32_16x16x32_bf16 v[74:77], v[164:167], v[78:81], v[74:77]
	v_add_f32_e32 v156, 0x41000000, v138
	v_cmp_gt_f32_e32 vcc, v151, v156
	s_cbranch_vccz .Lmla_s0_keep1
	v_max_f32_e32 v159, v138, v151
	v_sub_f32_e32 v156, v138, v159
	v_exp_f32_e32 v156, v156
	v_mov_b32_e32 v138, v159
	v_mul_f32_e32 v140, v140, v156
	v_pk_mul_f32 v[58:59], v[58:59], v[156:157] op_sel_hi:[1,0]
	v_pk_mul_f32 v[60:61], v[60:61], v[156:157] op_sel_hi:[1,0]
	v_pk_mul_f32 v[54:55], v[54:55], v[156:157] op_sel_hi:[1,0]
	v_pk_mul_f32 v[56:57], v[56:57], v[156:157] op_sel_hi:[1,0]
	v_pk_mul_f32 v[50:51], v[50:51], v[156:157] op_sel_hi:[1,0]
	v_pk_mul_f32 v[52:53], v[52:53], v[156:157] op_sel_hi:[1,0]
	v_pk_mul_f32 v[46:47], v[46:47], v[156:157] op_sel_hi:[1,0]
	v_pk_mul_f32 v[48:49], v[48:49], v[156:157] op_sel_hi:[1,0]
.Lmla_s0_keep1:
	v_fma_f32 v94, v94, s21, -v138
	v_fma_f32 v95, v95, s21, -v138
	v_exp_f32_e32 v94, v94
	v_fma_f32 v96, v96, s21, -v138
	v_exp_f32_e32 v95, v95
	v_fma_f32 v97, v97, s21, -v138
	v_exp_f32_e32 v96, v96
	s_waitcnt lgkmcnt(12)
	v_mfma_f32_16x16x32_bf16 v[70:73], v[168:171], v[78:81], v[70:73]
	v_exp_f32_e32 v97, v97
	v_fma_f32 v98, v98, s21, -v138
	v_fma_f32 v99, v99, s21, -v138
	v_exp_f32_e32 v98, v98
	v_fma_f32 v100, v100, s21, -v138
	v_exp_f32_e32 v99, v99
	v_fma_f32 v101, v101, s21, -v138
	v_exp_f32_e32 v100, v100
	s_waitcnt lgkmcnt(10)
	v_mfma_f32_16x16x32_bf16 v[74:77], v[172:175], v[82:85], v[74:77]
	v_exp_f32_e32 v101, v101
	v_add_f32_e32 v161, 0, v94
	v_add_f32_e32 v161, v95, v161
	v_add_f32_e32 v161, v96, v161
	v_add_f32_e32 v161, v97, v161
	v_cvt_pk_bf16_f32 v94, v94, v95
	v_cvt_pk_bf16_f32 v95, v96, v97
	v_fma_f32 v102, v102, s21, -v138
	s_waitcnt lgkmcnt(8)
	v_mfma_f32_16x16x32_bf16 v[70:73], v[176:179], v[82:85], v[70:73]
	v_fma_f32 v103, v103, s21, -v138
	v_exp_f32_e32 v102, v102
	v_fma_f32 v104, v104, s21, -v138
	v_exp_f32_e32 v103, v103
	v_fma_f32 v105, v105, s21, -v138
	v_exp_f32_e32 v104, v104
	v_exp_f32_e32 v105, v105
	v_add_f32_e32 v161, v98, v161
	s_waitcnt lgkmcnt(6)
	v_mfma_f32_16x16x32_bf16 v[66:69], v[232:235], v[78:81], v[66:69]
	v_add_f32_e32 v161, v99, v161
	v_add_f32_e32 v161, v100, v161
	v_add_f32_e32 v161, v101, v161
	v_cvt_pk_bf16_f32 v96, v98, v99
	v_cvt_pk_bf16_f32 v97, v100, v101
	v_fma_f32 v106, v106, s21, -v138
	v_fma_f32 v107, v107, s21, -v138
	v_exp_f32_e32 v106, v106
	s_waitcnt lgkmcnt(4)
	v_mfma_f32_16x16x32_bf16 v[62:65], v[236:239], v[78:81], v[62:65]
	v_fma_f32 v108, v108, s21, -v138
	v_exp_f32_e32 v107, v107
	v_fma_f32 v109, v109, s21, -v138
	v_exp_f32_e32 v108, v108
	v_exp_f32_e32 v109, v109
	v_add_f32_e32 v161, v102, v161
	v_add_f32_e32 v161, v103, v161
	v_add_f32_e32 v161, v104, v161
	s_waitcnt lgkmcnt(2)
	v_mfma_f32_16x16x32_bf16 v[66:69], v[240:243], v[82:85], v[66:69]
	v_add_f32_e32 v161, v105, v161
	v_cvt_pk_bf16_f32 v98, v102, v103
	v_cvt_pk_bf16_f32 v99, v104, v105
	v_add_f32_e32 v161, v106, v161
	v_add_f32_e32 v161, v107, v161
	v_add_f32_e32 v161, v108, v161
	v_add_f32_e32 v161, v109, v161
	v_cvt_pk_bf16_f32 v100, v106, v107
	s_waitcnt lgkmcnt(0)
	v_mfma_f32_16x16x32_bf16 v[62:65], v[244:247], v[82:85], v[62:65]
	v_cvt_pk_bf16_f32 v101, v108, v109
	v_add_f32_e32 v140, v140, v161
	v_mfma_f32_16x16x32_bf16 v[58:61], v[164:167], v[94:97], v[58:61]
	v_mfma_f32_16x16x32_bf16 v[54:57], v[168:171], v[94:97], v[54:57]
	v_mfma_f32_16x16x32_bf16 v[58:61], v[172:175], v[98:101], v[58:61]
	v_mfma_f32_16x16x32_bf16 v[54:57], v[176:179], v[98:101], v[54:57]
	v_mfma_f32_16x16x32_bf16 v[50:53], v[232:235], v[94:97], v[50:53]
	v_mfma_f32_16x16x32_bf16 v[46:49], v[236:239], v[94:97], v[46:49]
	v_mfma_f32_16x16x32_bf16 v[50:53], v[240:243], v[98:101], v[50:53]
	v_mfma_f32_16x16x32_bf16 v[46:49], v[244:247], v[98:101], v[46:49]
	v_add_u32_e32 v200, 0x2400, v200
	ds_read_b128 v[164:167], v201 offset:13312
	ds_read_b128 v[176:179], v201 offset:16640
	ds_read_b128 v[232:235], v201 offset:19968
	ds_read_b128 v[244:247], v201 offset:23296
	ds_read_b128 v[168:171], v201 offset:13376
	ds_read_b128 v[180:183], v201 offset:16704
	ds_read_b128 v[236:239], v201 offset:20032
	ds_read_b128 v[142:145], v201 offset:23360
	ds_read_b128 v[172:175], v201 offset:13440
	ds_read_b128 v[184:187], v201 offset:16768
	ds_read_b128 v[240:243], v201 offset:20096
	ds_read_b128 v[146:149], v201 offset:23424
	s_waitcnt lgkmcnt(11)
	v_mfma_f32_16x16x32_bf16 v[78:81], v[164:167], v[2:5], 0
	s_waitcnt lgkmcnt(10)
	v_mfma_f32_16x16x32_bf16 v[82:85], v[176:179], v[2:5], 0
	s_waitcnt lgkmcnt(9)
	v_mfma_f32_16x16x32_bf16 v[86:89], v[232:235], v[2:5], 0
	s_waitcnt lgkmcnt(8)
	v_mfma_f32_16x16x32_bf16 v[90:93], v[244:247], v[2:5], 0
	s_waitcnt lgkmcnt(7)
	v_mfma_f32_16x16x32_bf16 v[78:81], v[168:171], v[6:9], v[78:81]
	s_waitcnt lgkmcnt(6)
	v_mfma_f32_16x16x32_bf16 v[82:85], v[180:183], v[6:9], v[82:85]
	s_waitcnt lgkmcnt(5)
	v_mfma_f32_16x16x32_bf16 v[86:89], v[236:239], v[6:9], v[86:89]
	s_waitcnt lgkmcnt(4)
	v_mfma_f32_16x16x32_bf16 v[90:93], v[142:145], v[6:9], v[90:93]
	s_waitcnt lgkmcnt(3)
	v_mfma_f32_16x16x32_bf16 v[78:81], v[172:175], v[38:41], v[78:81]
	s_waitcnt lgkmcnt(2)
	v_mfma_f32_16x16x32_bf16 v[82:85], v[184:187], v[38:41], v[82:85]
	s_waitcnt lgkmcnt(1)
	v_mfma_f32_16x16x32_bf16 v[86:89], v[240:243], v[38:41], v[86:89]
	s_waitcnt lgkmcnt(0)
	v_mfma_f32_16x16x32_bf16 v[90:93], v[146:149], v[38:41], v[90:93]
	v_mfma_f32_16x16x32_bf16 v[94:97], v[164:167], v[26:29], 0
	s_nop 0
	v_max3_f32 v150, v78, s18, v79
	v_max3_f32 v150, v150, v80, v81
	v_max3_f32 v150, v150, v82, v83
	v_max3_f32 v150, v150, v84, v85
	v_max3_f32 v150, v150, v86, v87
	v_max3_f32 v150, v150, v88, v89
	v_max3_f32 v150, v150, v90, v91
	v_mfma_f32_16x16x32_bf16 v[98:101], v[176:179], v[26:29], 0
	v_max3_f32 v150, v150, v92, v93
	v_mul_f32_e32 v150, 0x3e16c740, v150
	v_mov_b32_e32 v152, v150
	s_nop 1
	v_permlane16_swap_b32_e32 v152, v150
	v_max_f32_e32 v150, v150, v152
	v_mov_b32_e32 v152, v150
	s_nop 1
	v_permlane32_swap_b32_e32 v152, v150
	v_mfma_f32_16x16x32_bf16 v[102:105], v[232:235], v[26:29], 0
	v_max_f32_e32 v150, v150, v152
	v_add_f32_e32 v154, 0x41000000, v139
	v_cmp_gt_f32_e32 vcc, v150, v154
	s_cbranch_vccz .Lmla_s1_keep0
	v_max_f32_e32 v158, v139, v150
	v_sub_f32_e32 v154, v139, v158
	v_exp_f32_e32 v154, v154
	v_mov_b32_e32 v139, v158
	v_mul_f32_e32 v141, v141, v154
	v_pk_mul_f32 v[74:75], v[74:75], v[154:155] op_sel_hi:[1,0]
	v_pk_mul_f32 v[76:77], v[76:77], v[154:155] op_sel_hi:[1,0]
	v_pk_mul_f32 v[70:71], v[70:71], v[154:155] op_sel_hi:[1,0]
	v_pk_mul_f32 v[72:73], v[72:73], v[154:155] op_sel_hi:[1,0]
	v_pk_mul_f32 v[66:67], v[66:67], v[154:155] op_sel_hi:[1,0]
	v_pk_mul_f32 v[68:69], v[68:69], v[154:155] op_sel_hi:[1,0]
	v_pk_mul_f32 v[62:63], v[62:63], v[154:155] op_sel_hi:[1,0]
	v_pk_mul_f32 v[64:65], v[64:65], v[154:155] op_sel_hi:[1,0]
